# load balancing: workgroups with 32 MoBA tiles run 7 chunk-prep tasks, those with 20 tiles run 9 (no grid barrier between the two phases)
# baseline (speedup 1.0000x reference)
.LBB0_370:
	s_or_b64 exec, exec, s[6:7]
	s_lshl_b32 s6, s24, 6
	s_ashr_i32 s5, s4, 31
	s_and_b32 s25, s6, 0x7c0
	s_lshl_b64 s[4:5], s[4:5], 18
	s_lshl_b32 s6, s25, 7
	s_or_b32 s4, s4, s6
	s_add_i32 s65, s24, s88
	s_and_b32 s32, s24, 0x718
	s_add_i32 s69, s24, 24
	s_cmp_eq_u32 s32, 0x700
	s_cselect_b32 s65, s69, s65
	s_and_b32 s32, s96, 0x18
	s_and_b32 s69, s65, 0xf00
	s_or_b32 s32, s32, s69
	s_cmp_eq_u32 s32, 0x718
	s_cselect_b32 s65, 0x800, s65
	s_cmpk_gt_i32 s65, 0x7ff
	s_cselect_b64 s[26:27], -1, 0
	s_cmpk_lt_i32 s65, 0x800
	v_and_b32_e32 v142, 15, v132
	v_ashrrev_i32_e32 v128, 4, v132
	s_cselect_b32 s31, s65, -1
	s_add_i32 s7, 0, 0x1f700
	v_lshlrev_b32_e32 v112, 2, v128
	v_lshl_add_u32 v97, v142, 5, 0
	s_waitcnt lgkmcnt(0)
	s_barrier
	v_add_u32_e32 v105, s7, v112
	v_add_u32_e32 v124, 0x20400, v97
	ds_read_b32 v96, v105
	ds_read_b128 v[100:103], v124 offset:1552
	ds_read_b128 v[108:111], v124 offset:16
	ds_read_b128 v[114:117], v124 offset:528
	ds_read_b128 v[118:121], v124 offset:1040
	v_lshlrev_b32_e32 v136, 16, v43
	v_and_b32_e32 v137, 0xffff0000, v43
	v_lshlrev_b32_e32 v126, 16, v51
	v_and_b32_e32 v127, 0xffff0000, v51
	s_waitcnt lgkmcnt(2)
	v_pk_fma_f32 v[136:137], v[110:111], v[136:137], 0 op_sel_hi:[1,1,0]
	v_lshlrev_b32_e32 v138, 16, v50
	v_and_b32_e32 v139, 0xffff0000, v50
	v_lshlrev_b32_e32 v122, 16, v63
	v_and_b32_e32 v123, 0xffff0000, v63
	v_pk_fma_f32 v[138:139], v[108:109], v[138:139], 0 op_sel_hi:[1,1,0]
	v_lshlrev_b32_e32 v146, 16, v3
	v_and_b32_e32 v147, 0xffff0000, v3
	s_waitcnt lgkmcnt(1)
	v_pk_fma_f32 v[126:127], v[116:117], v[126:127], v[136:137]
	v_lshlrev_b32_e32 v136, 16, v56
	v_and_b32_e32 v137, 0xffff0000, v56
	v_pk_fma_f32 v[146:147], v[110:111], v[146:147], 0 op_sel_hi:[1,1,0]
	v_lshlrev_b32_e32 v110, 16, v2
	v_and_b32_e32 v111, 0xffff0000, v2
	v_pk_fma_f32 v[136:137], v[114:115], v[136:137], v[138:139]
	v_lshlrev_b32_e32 v138, 16, v7
	v_and_b32_e32 v139, 0xffff0000, v7
	s_waitcnt lgkmcnt(0)
	v_pk_fma_f32 v[122:123], v[120:121], v[122:123], v[126:127]
	v_lshlrev_b32_e32 v126, 16, v64
	v_and_b32_e32 v127, 0xffff0000, v64
	v_pk_fma_f32 v[148:149], v[108:109], v[110:111], 0 op_sel_hi:[1,1,0]
	v_pk_fma_f32 v[138:139], v[116:117], v[138:139], v[146:147]
	v_lshlrev_b32_e32 v116, 16, v6
	v_and_b32_e32 v117, 0xffff0000, v6
	v_pk_fma_f32 v[126:127], v[118:119], v[126:127], v[136:137]
	v_lshlrev_b32_e32 v136, 16, v11
	v_and_b32_e32 v137, 0xffff0000, v11
	v_mov_b32_e32 v107, s23
	v_mul_f32_e32 v96, 0x3fb8aa3b, v96
	v_pk_fma_f32 v[146:147], v[114:115], v[116:117], v[148:149]
	v_pk_fma_f32 v[136:137], v[120:121], v[136:137], v[138:139]
	v_lshlrev_b32_e32 v120, 16, v10
	v_and_b32_e32 v121, 0xffff0000, v10
	v_exp_f32_e32 v106, v96
	ds_read_b128 v[96:99], v124 offset:512
	ds_read_b128 v[108:111], v124 offset:1024
	ds_read_b128 v[114:117], v124 offset:1536
	v_pk_fma_f32 v[138:139], v[118:119], v[120:121], v[146:147]
	ds_read_b32 v141, v107
	ds_read_b128 v[118:121], v124
	s_nop 0
	v_lshlrev_b32_e32 v146, 16, v19
	v_and_b32_e32 v147, 0xffff0000, v19
	v_lshlrev_b32_e32 v148, 16, v15
	v_and_b32_e32 v149, 0xffff0000, v15
	v_pk_fma_f32 v[122:123], v[102:103], v[146:147], v[122:123]
	v_lshlrev_b32_e32 v146, 16, v18
	v_and_b32_e32 v147, 0xffff0000, v18
	v_pk_fma_f32 v[102:103], v[102:103], v[148:149], v[136:137]
	v_lshlrev_b32_e32 v136, 16, v14
	v_and_b32_e32 v137, 0xffff0000, v14
	v_pk_fma_f32 v[126:127], v[100:101], v[146:147], v[126:127]
	v_pk_fma_f32 v[136:137], v[100:101], v[136:137], v[138:139]
	v_lshlrev_b32_e32 v100, 16, v40
	v_and_b32_e32 v101, 0xffff0000, v40
	v_lshlrev_b32_e32 v146, 16, v41
	v_and_b32_e32 v147, 0xffff0000, v41
	s_waitcnt lgkmcnt(0)
	v_pk_fma_f32 v[138:139], v[118:119], v[100:101], 0 op_sel_hi:[1,1,0]
	v_lshlrev_b32_e32 v100, 16, v1
	v_and_b32_e32 v101, 0xffff0000, v1
	v_pk_fma_f32 v[146:147], v[120:121], v[146:147], 0 op_sel_hi:[1,1,0]
	v_pk_fma_f32 v[120:121], v[120:121], v[100:101], 0 op_sel_hi:[1,1,0]
	v_lshlrev_b32_e32 v100, 16, v0
	v_and_b32_e32 v101, 0xffff0000, v0
	v_pk_fma_f32 v[118:119], v[118:119], v[100:101], 0 op_sel_hi:[1,1,0]
	v_mul_f32_e32 v100, 0xbfb8aa3b, v122
	v_exp_f32_e32 v100, v100
	v_mul_f32_e32 v101, 0xbfb8aa3b, v123
	v_exp_f32_e32 v101, v101
	v_and_b32_e32 v125, 64, v140
	v_add_f32_e32 v100, 1.0, v100
	v_rcp_f32_e32 v148, v100
	v_add_f32_e32 v100, 1.0, v101
	v_rcp_f32_e32 v149, v100
	v_xor_b32_e32 v113, 1, v140
	v_add_u32_e32 v107, 64, v125
	v_cmp_lt_i32_e32 vcc, v113, v107
	v_pk_mul_f32 v[122:123], v[122:123], v[148:149]
	v_lshlrev_b32_e32 v148, 16, v49
	v_and_b32_e32 v149, 0xffff0000, v49
	v_pk_fma_f32 v[146:147], v[98:99], v[148:149], v[146:147]
	v_lshlrev_b32_e32 v148, 16, v42
	v_and_b32_e32 v149, 0xffff0000, v42
	v_pk_fma_f32 v[138:139], v[96:97], v[148:149], v[138:139]
	v_lshlrev_b32_e32 v148, 16, v5
	v_and_b32_e32 v149, 0xffff0000, v5
	v_cndmask_b32_e32 v100, v140, v113, vcc
	v_mul_f32_e32 v113, 0xbfb8aa3b, v126
	v_pk_fma_f32 v[98:99], v[98:99], v[148:149], v[120:121]
	v_lshlrev_b32_e32 v120, 16, v4
	v_and_b32_e32 v121, 0xffff0000, v4
	v_exp_f32_e32 v113, v113
	v_pk_fma_f32 v[96:97], v[96:97], v[120:121], v[118:119]
	v_mul_f32_e32 v118, 0xbfb8aa3b, v127
	v_exp_f32_e32 v121, v118
	v_lshlrev_b32_e32 v148, 16, v57
	v_and_b32_e32 v149, 0xffff0000, v57
	v_pk_fma_f32 v[146:147], v[110:111], v[148:149], v[146:147]
	v_lshlrev_b32_e32 v148, 16, v17
	v_and_b32_e32 v149, 0xffff0000, v17
	v_pk_fma_f32 v[146:147], v[116:117], v[148:149], v[146:147]
	v_lshlrev_b32_e32 v148, 16, v48
	v_and_b32_e32 v149, 0xffff0000, v48
	v_add_f32_e32 v113, 1.0, v113
	v_pk_fma_f32 v[138:139], v[108:109], v[148:149], v[138:139]
	v_lshlrev_b32_e32 v148, 16, v16
	v_and_b32_e32 v149, 0xffff0000, v16
	v_rcp_f32_e32 v120, v113
	v_add_f32_e32 v113, 1.0, v121
	v_pk_fma_f32 v[138:139], v[114:115], v[148:149], v[138:139]
	v_lshlrev_b32_e32 v148, 16, v9
	v_and_b32_e32 v149, 0xffff0000, v9
	v_rcp_f32_e32 v121, v113
	v_mul_f32_e32 v113, 0xbfb8aa3b, v146
	v_pk_fma_f32 v[98:99], v[110:111], v[148:149], v[98:99]
	v_lshlrev_b32_e32 v110, 16, v8
	v_and_b32_e32 v111, 0xffff0000, v8
	v_exp_f32_e32 v113, v113
	v_mul_f32_e32 v125, 0xbfb8aa3b, v147
	v_pk_fma_f32 v[96:97], v[108:109], v[110:111], v[96:97]
	v_mul_f32_e32 v108, 0xbfb8aa3b, v138
	v_mul_f32_e32 v109, 0xbfb8aa3b, v139
	v_exp_f32_e32 v125, v125
	v_exp_f32_e32 v108, v108
	v_exp_f32_e32 v109, v109
	v_add_f32_e32 v113, 1.0, v113
	v_pk_mul_f32 v[120:121], v[126:127], v[120:121]
	v_rcp_f32_e32 v126, v113
	v_add_f32_e32 v113, 1.0, v125
	v_add_f32_e32 v108, 1.0, v108
	v_add_f32_e32 v109, 1.0, v109
	v_rcp_f32_e32 v127, v113
	v_rcp_f32_e32 v108, v108
	v_rcp_f32_e32 v109, v109
	v_mul_f32_e32 v113, 0xbfb8aa3b, v102
	v_exp_f32_e32 v113, v113
	v_mul_f32_e32 v125, 0xbfb8aa3b, v103
	v_exp_f32_e32 v125, v125
	v_pk_mul_f32 v[108:109], v[138:139], v[108:109]
	v_lshlrev_b32_e32 v138, 16, v13
	v_and_b32_e32 v139, 0xffff0000, v13
	v_pk_fma_f32 v[98:99], v[116:117], v[138:139], v[98:99]
	v_lshlrev_b32_e32 v116, 16, v12
	v_and_b32_e32 v117, 0xffff0000, v12
	v_add_f32_e32 v113, 1.0, v113
	v_pk_fma_f32 v[96:97], v[114:115], v[116:117], v[96:97]
	v_rcp_f32_e32 v116, v113
	v_add_f32_e32 v113, 1.0, v125
	v_rcp_f32_e32 v117, v113
	v_mul_f32_e32 v113, 0xbfb8aa3b, v136
	v_exp_f32_e32 v113, v113
	v_mul_f32_e32 v125, 0xbfb8aa3b, v137
	v_exp_f32_e32 v125, v125
	v_pk_mul_f32 v[102:103], v[102:103], v[116:117]
	v_add_f32_e32 v113, 1.0, v113
	v_mul_f32_e32 v117, 0xbfb8aa3b, v98
	v_rcp_f32_e32 v116, v113
	v_add_f32_e32 v113, 1.0, v125
	v_exp_f32_e32 v125, v117
	v_mul_f32_e32 v117, 0xbfb8aa3b, v99
	v_exp_f32_e32 v130, v117
	v_rcp_f32_e32 v117, v113
	v_add_f32_e32 v113, 1.0, v125
	v_mul_f32_e32 v125, 0xbfb8aa3b, v96
	v_rcp_f32_e32 v138, v113
	v_add_f32_e32 v113, 1.0, v130
	v_exp_f32_e32 v125, v125
	v_mul_f32_e32 v130, 0xbfb8aa3b, v97
	v_exp_f32_e32 v130, v130
	v_rcp_f32_e32 v139, v113
	v_add_f32_e32 v113, 1.0, v125
	v_rcp_f32_e32 v148, v113
	v_add_f32_e32 v113, 1.0, v130
	v_rcp_f32_e32 v149, v113
	v_pk_mul_f32 v[126:127], v[146:147], v[126:127]
	v_pk_mul_f32 v[114:115], v[108:109], v[108:109]
	v_pk_mul_f32 v[150:151], v[98:99], v[138:139]
	v_pk_mul_f32 v[148:149], v[96:97], v[148:149]
	v_pk_mul_f32 v[146:147], v[126:127], v[126:127]
	v_pk_mul_f32 v[96:97], v[148:149], v[148:149]
	v_mov_b32_e32 v99, v114
	v_mov_b32_e32 v98, v96
	v_mov_b32_e32 v114, v97
	v_pk_mul_f32 v[96:97], v[150:151], v[150:151]
	v_pk_mul_f32 v[136:137], v[136:137], v[116:117]
	v_pk_add_f32 v[98:99], v[98:99], v[114:115]
	v_mov_b32_e32 v114, v96
	v_mov_b32_e32 v115, v146
	v_pk_mul_f32 v[110:111], v[120:121], v[120:121]
	v_pk_add_f32 v[98:99], v[98:99], v[114:115]
	v_pk_mul_f32 v[114:115], v[136:137], v[136:137]
	v_mov_b32_e32 v146, v97
	v_pk_add_f32 v[96:97], v[98:99], v[146:147]
	v_mov_b32_e32 v98, v114
	v_mov_b32_e32 v99, v110
	v_pk_mul_f32 v[118:119], v[122:123], v[122:123]
	v_pk_mul_f32 v[116:117], v[102:103], v[102:103]
	v_pk_add_f32 v[96:97], v[96:97], v[98:99]
	v_mov_b32_e32 v110, v115
	v_pk_add_f32 v[96:97], v[96:97], v[110:111]
	v_mov_b32_e32 v98, v116
	v_mov_b32_e32 v99, v118
	v_pk_add_f32 v[96:97], v[96:97], v[98:99]
	v_mov_b32_e32 v118, v117
	v_lshlrev_b32_e32 v101, 2, v100
	v_pk_add_f32 v[96:97], v[96:97], v[118:119]
	ds_bpermute_b32 v99, v101, v97
	ds_bpermute_b32 v98, v101, v96
	v_xor_b32_e32 v100, 2, v140
	v_cmp_lt_i32_e32 vcc, v100, v107
	v_lshl_add_u32 v104, v142, 4, 0
	v_mad_u64_u32 v[138:139], s[8:9], v128, s33, v[104:105]
	v_cndmask_b32_e32 v100, v140, v100, vcc
	v_lshlrev_b32_e32 v113, 2, v100
	s_waitcnt lgkmcnt(0)
	v_pk_add_f32 v[96:97], v[96:97], v[98:99]
	ds_bpermute_b32 v99, v113, v97
	ds_bpermute_b32 v98, v113, v96
	v_xor_b32_e32 v100, 4, v140
	v_cmp_lt_i32_e32 vcc, v100, v107
	s_add_i32 s6, 0, 0x1f800
	s_lshl_b64 s[28:29], s[4:5], 1
	v_cndmask_b32_e32 v100, v140, v100, vcc
	v_lshlrev_b32_e32 v115, 2, v100
	s_waitcnt lgkmcnt(0)
	v_pk_add_f32 v[96:97], v[96:97], v[98:99]
	ds_bpermute_b32 v99, v115, v97
	ds_bpermute_b32 v98, v115, v96
	v_xor_b32_e32 v100, 8, v140
	v_cmp_lt_i32_e32 vcc, v100, v107
	s_add_u32 s4, s42, s28
	s_addc_u32 s5, s43, s29
	v_cndmask_b32_e32 v100, v140, v100, vcc
	v_lshlrev_b32_e32 v116, 2, v100
	s_waitcnt lgkmcnt(0)
	v_pk_add_f32 v[96:97], v[96:97], v[98:99]
	ds_bpermute_b32 v99, v116, v97
	ds_bpermute_b32 v98, v116, v96
	v_add_u32_e32 v100, 0x200, v132
	v_ashrrev_i32_e32 v134, 4, v100
	v_lshlrev_b32_e32 v117, 2, v134
	v_add_u32_e32 v114, s7, v117
	s_waitcnt lgkmcnt(0)
	v_pk_add_f32 v[96:97], v[96:97], v[98:99]
	v_ashrrev_i32_e32 v133, 31, v132
	v_pk_add_f32 v[110:111], v[96:97], s[22:23] op_sel_hi:[1,0]
	v_lshl_add_u64 v[146:147], v[132:133], 4, s[4:5]
	v_mul_f32_e32 v96, 0x4b800000, v111
	v_cmp_gt_f32_e32 vcc, s36, v111
	v_lshlrev_b32_e32 v154, 16, v79
	v_and_b32_e32 v155, 0xffff0000, v79
	v_cndmask_b32_e32 v96, v111, v96, vcc
	v_rsq_f32_e32 v96, v96
	v_lshlrev_b32_e32 v160, 16, v83
	v_and_b32_e32 v161, 0xffff0000, v83
	v_lshlrev_b32_e32 v168, 16, v23
	v_mul_f32_e32 v97, 0x45800000, v96
	v_cndmask_b32_e32 v96, v96, v97, vcc
	v_mul_f32_e32 v96, 0x3db504f3, v96
	v_pk_mul_f32 v[108:109], v[108:109], v[96:97] op_sel_hi:[1,0]
	v_pk_mul_f32 v[126:127], v[126:127], v[96:97] op_sel_hi:[1,0]
	v_pk_mul_f32 v[120:121], v[120:121], v[96:97] op_sel_hi:[1,0]
	v_pk_mul_f32 v[122:123], v[122:123], v[96:97] op_sel_hi:[1,0]
	v_cvt_pk_bf16_f32 v96, v108, v109
	v_cvt_pk_bf16_f32 v97, v126, v127
	v_cvt_pk_bf16_f32 v98, v120, v121
	v_cvt_pk_bf16_f32 v99, v122, v123
	ds_write_b128 v138, v[96:99]
	v_mul_f32_e32 v98, 0x4b800000, v110
	v_cmp_gt_f32_e32 vcc, s36, v110
	v_pk_mul_f32 v[96:97], v[106:107], v[108:109] op_sel_hi:[0,1]
	v_cvt_pk_bf16_f32 v118, v96, v97
	v_cndmask_b32_e32 v98, v110, v98, vcc
	v_rsq_f32_e32 v98, v98
	v_pk_mul_f32 v[96:97], v[106:107], v[126:127] op_sel_hi:[0,1]
	v_cvt_pk_bf16_f32 v119, v96, v97
	v_pk_mul_f32 v[96:97], v[106:107], v[120:121] op_sel_hi:[0,1]
	v_cvt_pk_bf16_f32 v120, v96, v97
	v_mul_f32_e32 v96, 0x45800000, v98
	v_cndmask_b32_e32 v96, v98, v96, vcc
	v_mul_f32_e32 v96, 0x3db504f3, v96
	v_pk_mul_f32 v[122:123], v[106:107], v[122:123] op_sel_hi:[0,1]
	v_pk_mul_f32 v[108:109], v[148:149], v[96:97] op_sel_hi:[1,0]
	v_pk_mul_f32 v[110:111], v[150:151], v[96:97] op_sel_hi:[1,0]
	v_pk_mul_f32 v[106:107], v[136:137], v[96:97] op_sel_hi:[1,0]
	v_pk_mul_f32 v[102:103], v[102:103], v[96:97] op_sel_hi:[1,0]
	v_cvt_pk_bf16_f32 v96, v108, v109
	v_cvt_pk_bf16_f32 v97, v110, v111
	v_cvt_pk_bf16_f32 v98, v106, v107
	v_cvt_pk_bf16_f32 v99, v102, v103
	v_mad_u64_u32 v[136:137], s[8:9], v134, s33, v[104:105]
	ds_read_b32 v125, v114
	ds_write_b128 v136, v[96:99]
	ds_read_b128 v[96:99], v124 offset:2064
	v_cvt_pk_bf16_f32 v121, v122, v123
	global_store_dwordx4 v[146:147], v[118:121], off
	v_lshlrev_b32_e32 v122, 16, v71
	v_and_b32_e32 v123, 0xffff0000, v71
	v_lshlrev_b32_e32 v146, 16, v27
	v_and_b32_e32 v147, 0xffff0000, v27
	ds_read_b128 v[118:121], v124 offset:2048
	s_waitcnt lgkmcnt(1)
	v_pk_fma_f32 v[122:123], v[98:99], v[122:123], 0 op_sel_hi:[1,1,0]
	v_lshlrev_b32_e32 v126, 16, v80
	v_and_b32_e32 v127, 0xffff0000, v80
	v_pk_fma_f32 v[150:151], v[98:99], v[146:147], 0 op_sel_hi:[1,1,0]
	v_lshlrev_b32_e32 v98, 16, v26
	v_and_b32_e32 v99, 0xffff0000, v26
	v_pk_fma_f32 v[126:127], v[96:97], v[126:127], 0 op_sel_hi:[1,1,0]
	v_pk_fma_f32 v[152:153], v[96:97], v[98:99], 0 op_sel_hi:[1,1,0]
	ds_read_b128 v[96:99], v124 offset:2576
	ds_read_b128 v[146:149], v124 offset:2560
	v_and_b32_e32 v169, 0xffff0000, v23
	v_add_u32_e32 v130, s6, v112
	v_add_u32_e32 v137, s6, v117
	s_waitcnt lgkmcnt(1)
	v_pk_fma_f32 v[122:123], v[98:99], v[154:155], v[122:123]
	v_lshlrev_b32_e32 v154, 16, v84
	v_and_b32_e32 v155, 0xffff0000, v84
	v_pk_fma_f32 v[126:127], v[96:97], v[154:155], v[126:127]
	v_lshlrev_b32_e32 v154, 16, v31
	v_and_b32_e32 v155, 0xffff0000, v31
	v_pk_fma_f32 v[154:155], v[98:99], v[154:155], v[150:151]
	v_lshlrev_b32_e32 v98, 16, v30
	v_and_b32_e32 v99, 0xffff0000, v30
	v_pk_fma_f32 v[158:159], v[96:97], v[98:99], v[152:153]
	ds_read_b128 v[96:99], v124 offset:3088
	ds_read_b128 v[150:153], v124 offset:3072
	s_cmp_lt_i32 s31, 0
	s_waitcnt lgkmcnt(1)
	v_pk_fma_f32 v[122:123], v[98:99], v[160:161], v[122:123]
	v_lshlrev_b32_e32 v160, 16, v88
	v_and_b32_e32 v161, 0xffff0000, v88
	v_pk_fma_f32 v[126:127], v[96:97], v[160:161], v[126:127]
	v_lshlrev_b32_e32 v160, 16, v35
	v_and_b32_e32 v161, 0xffff0000, v35
	v_pk_fma_f32 v[154:155], v[98:99], v[160:161], v[154:155]
	v_lshlrev_b32_e32 v98, 16, v34
	v_and_b32_e32 v99, 0xffff0000, v34
	v_pk_fma_f32 v[162:163], v[96:97], v[98:99], v[158:159]
	ds_read_b128 v[96:99], v124 offset:3600
	ds_read_b128 v[158:161], v124 offset:3584
	ds_read_b32 v112, v105
	s_waitcnt lgkmcnt(2)
	v_pk_fma_f32 v[122:123], v[98:99], v[168:169], v[122:123]
	v_lshlrev_b32_e32 v168, 16, v22
	v_and_b32_e32 v169, 0xffff0000, v22
	v_pk_fma_f32 v[126:127], v[96:97], v[168:169], v[126:127]
	v_lshlrev_b32_e32 v168, 16, v39
	v_and_b32_e32 v169, 0xffff0000, v39
	v_pk_fma_f32 v[154:155], v[98:99], v[168:169], v[154:155]
	v_lshlrev_b32_e32 v98, 16, v38
	v_and_b32_e32 v99, 0xffff0000, v38
	v_pk_fma_f32 v[162:163], v[96:97], v[98:99], v[162:163]
	v_lshlrev_b32_e32 v96, 16, v65
	v_and_b32_e32 v97, 0xffff0000, v65
	v_lshlrev_b32_e32 v168, 16, v25
	v_and_b32_e32 v169, 0xffff0000, v25
	v_pk_fma_f32 v[96:97], v[120:121], v[96:97], 0 op_sel_hi:[1,1,0]
	v_lshlrev_b32_e32 v98, 16, v62
	v_and_b32_e32 v99, 0xffff0000, v62
	v_pk_fma_f32 v[120:121], v[120:121], v[168:169], 0 op_sel_hi:[1,1,0]
	v_lshlrev_b32_e32 v168, 16, v24
	v_and_b32_e32 v169, 0xffff0000, v24
	v_pk_fma_f32 v[98:99], v[118:119], v[98:99], 0 op_sel_hi:[1,1,0]
	v_pk_fma_f32 v[118:119], v[118:119], v[168:169], 0 op_sel_hi:[1,1,0]
	v_lshlrev_b32_e32 v168, 16, v77
	v_and_b32_e32 v169, 0xffff0000, v77
	v_pk_fma_f32 v[96:97], v[148:149], v[168:169], v[96:97]
	v_lshlrev_b32_e32 v168, 16, v70
	v_and_b32_e32 v169, 0xffff0000, v70
	v_pk_fma_f32 v[98:99], v[146:147], v[168:169], v[98:99]
	v_lshlrev_b32_e32 v168, 16, v29
	v_and_b32_e32 v169, 0xffff0000, v29
	v_pk_fma_f32 v[120:121], v[148:149], v[168:169], v[120:121]
	v_lshlrev_b32_e32 v148, 16, v28
	v_and_b32_e32 v149, 0xffff0000, v28
	v_pk_fma_f32 v[118:119], v[146:147], v[148:149], v[118:119]
	v_lshlrev_b32_e32 v146, 16, v81
	v_and_b32_e32 v147, 0xffff0000, v81
	v_pk_fma_f32 v[96:97], v[152:153], v[146:147], v[96:97]
	v_lshlrev_b32_e32 v146, 16, v76
	v_and_b32_e32 v147, 0xffff0000, v76
	v_pk_fma_f32 v[98:99], v[150:151], v[146:147], v[98:99]
	v_lshlrev_b32_e32 v146, 16, v33
	v_and_b32_e32 v147, 0xffff0000, v33
	v_pk_fma_f32 v[120:121], v[152:153], v[146:147], v[120:121]
	v_lshlrev_b32_e32 v146, 16, v32
	v_and_b32_e32 v147, 0xffff0000, v32
	v_pk_fma_f32 v[118:119], v[150:151], v[146:147], v[118:119]
	v_lshlrev_b32_e32 v146, 16, v21
	v_and_b32_e32 v147, 0xffff0000, v21
	s_waitcnt lgkmcnt(1)
	v_pk_fma_f32 v[146:147], v[160:161], v[146:147], v[96:97]
	v_lshlrev_b32_e32 v96, 16, v20
	v_and_b32_e32 v97, 0xffff0000, v20
	v_pk_fma_f32 v[148:149], v[158:159], v[96:97], v[98:99]
	v_lshlrev_b32_e32 v96, 16, v37
	v_and_b32_e32 v97, 0xffff0000, v37
	v_pk_fma_f32 v[120:121], v[160:161], v[96:97], v[120:121]
	v_lshlrev_b32_e32 v96, 16, v36
	v_and_b32_e32 v97, 0xffff0000, v36
	v_pk_fma_f32 v[118:119], v[158:159], v[96:97], v[118:119]
	v_mul_f32_e32 v96, 0x3fb8aa3b, v125
	v_exp_f32_e32 v104, v96
	s_nop 0
	v_pk_mul_f32 v[96:97], v[104:105], v[108:109] op_sel_hi:[0,1]
	v_pk_mul_f32 v[98:99], v[104:105], v[110:111] op_sel_hi:[0,1]
	v_cvt_pk_bf16_f32 v96, v96, v97
	v_cvt_pk_bf16_f32 v97, v98, v99
	v_pk_mul_f32 v[98:99], v[104:105], v[106:107] op_sel_hi:[0,1]
	v_cvt_pk_bf16_f32 v98, v98, v99
	v_pk_mul_f32 v[102:103], v[104:105], v[102:103] op_sel_hi:[0,1]
	v_mul_f32_e32 v99, 0xbfb8aa3b, v122
	v_mul_f32_e32 v104, 0xbfb8aa3b, v123
	v_exp_f32_e32 v99, v99
	v_exp_f32_e32 v104, v104
	v_add_f32_e32 v99, 1.0, v99
	v_add_f32_e32 v104, 1.0, v104
	v_rcp_f32_e32 v106, v99
	v_rcp_f32_e32 v107, v104
	v_mul_f32_e32 v99, 0xbfb8aa3b, v126
	v_mul_f32_e32 v104, 0xbfb8aa3b, v127
	v_exp_f32_e32 v99, v99
	v_exp_f32_e32 v104, v104
	v_pk_mul_f32 v[106:107], v[122:123], v[106:107]
	v_add_f32_e32 v99, 1.0, v99
	v_add_f32_e32 v104, 1.0, v104
	v_rcp_f32_e32 v108, v99
	v_rcp_f32_e32 v109, v104
	v_mul_f32_e32 v99, 0xbfb8aa3b, v146
	v_mul_f32_e32 v104, 0xbfb8aa3b, v147
	v_exp_f32_e32 v99, v99
	v_exp_f32_e32 v104, v104
	v_pk_mul_f32 v[108:109], v[126:127], v[108:109]
	v_add_f32_e32 v99, 1.0, v99
	v_add_f32_e32 v104, 1.0, v104
	v_rcp_f32_e32 v110, v99
	v_rcp_f32_e32 v111, v104
	v_mul_f32_e32 v99, 0xbfb8aa3b, v148
	v_mul_f32_e32 v104, 0xbfb8aa3b, v149
	v_exp_f32_e32 v99, v99
	v_exp_f32_e32 v104, v104
	v_pk_mul_f32 v[110:111], v[146:147], v[110:111]
	v_add_f32_e32 v99, 1.0, v99
	v_add_f32_e32 v104, 1.0, v104
	v_rcp_f32_e32 v122, v99
	v_rcp_f32_e32 v123, v104
	v_mul_f32_e32 v99, 0xbfb8aa3b, v154
	v_mul_f32_e32 v104, 0xbfb8aa3b, v155
	v_exp_f32_e32 v99, v99
	v_exp_f32_e32 v104, v104
	v_pk_mul_f32 v[122:123], v[148:149], v[122:123]
	v_add_f32_e32 v99, 1.0, v99
	v_add_f32_e32 v104, 1.0, v104
	v_rcp_f32_e32 v126, v99
	v_rcp_f32_e32 v127, v104
	v_mul_f32_e32 v99, 0xbfb8aa3b, v162
	v_mul_f32_e32 v104, 0xbfb8aa3b, v163
	v_exp_f32_e32 v99, v99
	v_exp_f32_e32 v104, v104
	v_pk_mul_f32 v[126:127], v[154:155], v[126:127]
	v_add_f32_e32 v99, 1.0, v99
	v_add_f32_e32 v104, 1.0, v104
	v_rcp_f32_e32 v146, v99
	v_rcp_f32_e32 v147, v104
	v_mul_f32_e32 v99, 0xbfb8aa3b, v120
	v_mul_f32_e32 v104, 0xbfb8aa3b, v121
	v_exp_f32_e32 v99, v99
	v_exp_f32_e32 v104, v104
	v_pk_mul_f32 v[146:147], v[162:163], v[146:147]
	v_add_f32_e32 v99, 1.0, v99
	v_add_f32_e32 v104, 1.0, v104
	v_rcp_f32_e32 v148, v99
	v_rcp_f32_e32 v149, v104
	v_mul_f32_e32 v99, 0xbfb8aa3b, v118
	v_mul_f32_e32 v104, 0xbfb8aa3b, v119
	v_exp_f32_e32 v99, v99
	v_exp_f32_e32 v104, v104
	v_pk_mul_f32 v[120:121], v[120:121], v[148:149]
	v_add_f32_e32 v99, 1.0, v99
	v_add_f32_e32 v104, 1.0, v104
	v_rcp_f32_e32 v148, v99
	v_rcp_f32_e32 v149, v104
	v_cvt_pk_bf16_f32 v99, v102, v103
	v_pk_mul_f32 v[118:119], v[118:119], v[148:149]
	v_pk_mul_f32 v[148:149], v[122:123], v[122:123]
	v_pk_mul_f32 v[150:151], v[118:119], v[118:119]
	v_mov_b32_e32 v153, v148
	v_mov_b32_e32 v152, v150
	v_mov_b32_e32 v148, v151
	v_pk_add_f32 v[148:149], v[152:153], v[148:149]
	v_pk_mul_f32 v[150:151], v[110:111], v[110:111]
	v_pk_mul_f32 v[152:153], v[120:121], v[120:121]
	v_mov_b32_e32 v155, v150
	v_mov_b32_e32 v154, v152
	v_pk_add_f32 v[148:149], v[148:149], v[154:155]
	v_mov_b32_e32 v150, v153
	v_pk_add_f32 v[148:149], v[148:149], v[150:151]
	v_pk_mul_f32 v[150:151], v[108:109], v[108:109]
	v_pk_mul_f32 v[152:153], v[146:147], v[146:147]
	v_mov_b32_e32 v155, v150
	v_mov_b32_e32 v154, v152
	v_pk_add_f32 v[148:149], v[148:149], v[154:155]
	v_mov_b32_e32 v150, v153
	v_pk_add_f32 v[148:149], v[148:149], v[150:151]
	v_pk_mul_f32 v[150:151], v[106:107], v[106:107]
	v_pk_mul_f32 v[152:153], v[126:127], v[126:127]
	v_mov_b32_e32 v155, v150
	v_mov_b32_e32 v154, v152
	v_pk_add_f32 v[148:149], v[148:149], v[154:155]
	v_mov_b32_e32 v150, v153
	v_pk_add_f32 v[148:149], v[148:149], v[150:151]
	ds_bpermute_b32 v151, v101, v149
	ds_bpermute_b32 v150, v101, v148
	v_ashrrev_i32_e32 v101, 31, v100
	v_lshl_add_u64 v[100:101], v[100:101], 4, s[4:5]
	global_store_dwordx4 v[100:101], v[96:99], off
	v_lshlrev_b32_e32 v152, 16, v87
	s_waitcnt lgkmcnt(0)
	v_pk_add_f32 v[148:149], v[148:149], v[150:151]
	ds_bpermute_b32 v151, v113, v149
	ds_bpermute_b32 v150, v113, v148
	ds_read_b32 v113, v130
	v_mul_f32_e32 v112, 0x3fb8aa3b, v112
	v_exp_f32_e32 v112, v112
	v_and_b32_e32 v153, 0xffff0000, v87
	s_waitcnt lgkmcnt(1)
	v_pk_add_f32 v[148:149], v[148:149], v[150:151]
	ds_bpermute_b32 v151, v115, v149
	ds_bpermute_b32 v150, v115, v148
	s_waitcnt lgkmcnt(2)
	v_mul_f32_e32 v100, v113, v112
	s_waitcnt lgkmcnt(0)
	v_pk_add_f32 v[102:103], v[148:149], v[150:151]
	ds_bpermute_b32 v105, v116, v103
	ds_bpermute_b32 v104, v116, v102
	s_nop 0
	v_lshlrev_b32_e32 v148, 16, v44
	v_and_b32_e32 v149, 0xffff0000, v44
	v_lshlrev_b32_e32 v150, 16, v85
	v_and_b32_e32 v151, 0xffff0000, v85
	s_waitcnt lgkmcnt(0)
	v_pk_add_f32 v[102:103], v[102:103], v[104:105]
	s_nop 0
	v_pk_add_f32 v[102:103], v[102:103], s[22:23] op_sel_hi:[1,0]
	s_nop 0
	v_mul_f32_e32 v104, 0x4b800000, v103
	v_cmp_gt_f32_e32 vcc, s36, v103
	s_nop 1
	v_cndmask_b32_e32 v103, v103, v104, vcc
	v_rsq_f32_e32 v103, v103
	s_nop 0
	v_mul_f32_e32 v96, 0x45800000, v103
	v_cndmask_b32_e32 v96, v103, v96, vcc
	v_pk_mul_f32 v[104:105], v[122:123], v[96:97] op_sel_hi:[1,0]
	v_pk_mul_f32 v[110:111], v[110:111], v[96:97] op_sel_hi:[1,0]
	v_pk_mul_f32 v[108:109], v[108:109], v[96:97] op_sel_hi:[1,0]
	v_pk_mul_f32 v[106:107], v[106:107], v[96:97] op_sel_hi:[1,0]
	v_cvt_pk_bf16_f32 v96, v104, v105
	v_cvt_pk_bf16_f32 v97, v110, v111
	v_cvt_pk_bf16_f32 v98, v108, v109
	v_cvt_pk_bf16_f32 v99, v106, v107
	ds_write_b128 v138, v[96:99] offset:17408
	v_pk_mul_f32 v[96:97], v[100:101], v[104:105] op_sel_hi:[0,1]
	v_pk_mul_f32 v[98:99], v[100:101], v[110:111] op_sel_hi:[0,1]
	v_cvt_pk_bf16_f32 v96, v96, v97
	v_cvt_pk_bf16_f32 v97, v98, v99
	v_pk_mul_f32 v[98:99], v[100:101], v[108:109] op_sel_hi:[0,1]
	v_pk_mul_f32 v[100:101], v[100:101], v[106:107] op_sel_hi:[0,1]
	v_cvt_pk_bf16_f32 v98, v98, v99
	v_cvt_pk_bf16_f32 v99, v100, v101
	ds_write_b128 v138, v[96:99] offset:52224
	ds_read_b32 v96, v114
	ds_read_b32 v108, v137
	v_mul_f32_e32 v97, 0x4b800000, v102
	v_cmp_gt_f32_e32 vcc, s36, v102
	s_waitcnt lgkmcnt(1)
	v_mul_f32_e32 v96, 0x3fb8aa3b, v96
	v_cndmask_b32_e32 v97, v102, v97, vcc
	v_rsq_f32_e32 v97, v97
	v_exp_f32_e32 v109, v96
	v_mul_f32_e32 v96, 0x45800000, v97
	v_cndmask_b32_e32 v96, v97, v96, vcc
	v_pk_mul_f32 v[100:101], v[118:119], v[96:97] op_sel_hi:[1,0]
	v_pk_mul_f32 v[102:103], v[120:121], v[96:97] op_sel_hi:[1,0]
	v_pk_mul_f32 v[104:105], v[146:147], v[96:97] op_sel_hi:[1,0]
	v_pk_mul_f32 v[106:107], v[126:127], v[96:97] op_sel_hi:[1,0]
	v_cvt_pk_bf16_f32 v96, v100, v101
	v_cvt_pk_bf16_f32 v97, v102, v103
	v_cvt_pk_bf16_f32 v98, v104, v105
	v_cvt_pk_bf16_f32 v99, v106, v107
	s_waitcnt lgkmcnt(0)
	v_mul_f32_e32 v108, v108, v109
	ds_write_b128 v136, v[96:99] offset:17408
	v_pk_mul_f32 v[96:97], v[108:109], v[100:101] op_sel_hi:[0,1]
	v_pk_mul_f32 v[98:99], v[108:109], v[102:103] op_sel_hi:[0,1]
	v_cvt_pk_bf16_f32 v96, v96, v97
	v_cvt_pk_bf16_f32 v97, v98, v99
	v_pk_mul_f32 v[98:99], v[108:109], v[104:105] op_sel_hi:[0,1]
	v_pk_mul_f32 v[100:101], v[108:109], v[106:107] op_sel_hi:[0,1]
	v_cvt_pk_bf16_f32 v98, v98, v99
	v_cvt_pk_bf16_f32 v99, v100, v101
	ds_write_b128 v136, v[96:99] offset:52224
	ds_read_b128 v[120:123], v124 offset:4096
	ds_read_b128 v[96:99], v124 offset:4112
	ds_read_b128 v[112:115], v124 offset:4608
	ds_read_b128 v[100:103], v124 offset:5120
	ds_read_b128 v[108:111], v124 offset:5632
	v_lshlrev_b32_e32 v104, 16, v78
	v_and_b32_e32 v105, 0xffff0000, v78
	s_waitcnt lgkmcnt(4)
	v_pk_fma_f32 v[116:117], v[120:121], v[104:105], 0 op_sel_hi:[1,1,0]
	v_lshlrev_b32_e32 v118, 16, v82
	v_and_b32_e32 v119, 0xffff0000, v82
	s_waitcnt lgkmcnt(2)
	v_pk_fma_f32 v[126:127], v[112:113], v[118:119], v[116:117]
	v_lshlrev_b32_e32 v146, 16, v86
	v_and_b32_e32 v147, 0xffff0000, v86
	s_waitcnt lgkmcnt(1)
	v_pk_fma_f32 v[146:147], v[100:101], v[146:147], v[126:127]
	v_pk_fma_f32 v[150:151], v[122:123], v[150:151], 0 op_sel_hi:[1,1,0]
	s_waitcnt lgkmcnt(0)
	v_pk_fma_f32 v[146:147], v[108:109], v[148:149], v[146:147]
	ds_read_b128 v[104:107], v124 offset:4624
	ds_read_b128 v[116:119], v124 offset:5136
	v_mul_f32_e32 v139, 0xbfb8aa3b, v147
	v_mul_f32_e32 v148, 0xbfb8aa3b, v146
	v_exp_f32_e32 v139, v139
	v_exp_f32_e32 v148, v148
	ds_read_b128 v[124:127], v124 offset:5648
	ds_read_b32 v130, v130
	v_add_f32_e32 v139, 1.0, v139
	v_add_f32_e32 v148, 1.0, v148
	v_rcp_f32_e32 v149, v139
	v_rcp_f32_e32 v148, v148
	v_pk_fma_f32 v[152:153], v[98:99], v[152:153], 0 op_sel_hi:[1,1,0]
	v_pk_mul_f32 v[146:147], v[146:147], v[148:149]
	v_lshlrev_b32_e32 v148, 16, v89
	v_and_b32_e32 v149, 0xffff0000, v89
	v_pk_fma_f32 v[148:149], v[114:115], v[148:149], v[150:151]
	v_lshlrev_b32_e32 v150, 16, v93
	v_and_b32_e32 v151, 0xffff0000, v93
	v_pk_fma_f32 v[148:149], v[102:103], v[150:151], v[148:149]
	v_lshlrev_b32_e32 v150, 16, v45
	v_and_b32_e32 v151, 0xffff0000, v45
	v_pk_fma_f32 v[148:149], v[110:111], v[150:151], v[148:149]
	s_waitcnt lgkmcnt(0)
	v_pk_mul_f32 v[146:147], v[130:131], v[146:147] op_sel_hi:[0,1]
	v_mul_f32_e32 v139, 0xbfb8aa3b, v149
	v_mul_f32_e32 v150, 0xbfb8aa3b, v148
	v_exp_f32_e32 v139, v139
	v_exp_f32_e32 v150, v150
	v_cvt_pk_bf16_f32 v146, v146, v147
	v_add_f32_e32 v139, 1.0, v139
	v_add_f32_e32 v150, 1.0, v150
	v_rcp_f32_e32 v151, v139
	v_rcp_f32_e32 v150, v150
	s_nop 0
	v_pk_mul_f32 v[148:149], v[148:149], v[150:151]
	s_nop 0
	v_pk_mul_f32 v[148:149], v[130:131], v[148:149] op_sel_hi:[0,1]
	v_lshlrev_b32_e32 v150, 16, v90
	v_and_b32_e32 v151, 0xffff0000, v90
	v_cvt_pk_bf16_f32 v147, v148, v149
	v_lshlrev_b32_e32 v148, 16, v92
	v_and_b32_e32 v149, 0xffff0000, v92
	v_pk_fma_f32 v[150:151], v[96:97], v[150:151], 0 op_sel_hi:[1,1,0]
	s_nop 0
	v_pk_fma_f32 v[148:149], v[104:105], v[148:149], v[150:151]
	v_lshlrev_b32_e32 v150, 16, v94
	v_and_b32_e32 v151, 0xffff0000, v94
	v_pk_fma_f32 v[148:149], v[116:117], v[150:151], v[148:149]
	v_lshlrev_b32_e32 v150, 16, v46
	v_and_b32_e32 v151, 0xffff0000, v46
	v_pk_fma_f32 v[148:149], v[124:125], v[150:151], v[148:149]
	s_nop 0
	v_mul_f32_e32 v139, 0xbfb8aa3b, v149
	v_mul_f32_e32 v150, 0xbfb8aa3b, v148
	v_exp_f32_e32 v139, v139
	v_exp_f32_e32 v150, v150
	v_add_f32_e32 v139, 1.0, v139
	v_add_f32_e32 v150, 1.0, v150
	v_rcp_f32_e32 v151, v139
	v_rcp_f32_e32 v150, v150
	s_nop 0
	v_pk_mul_f32 v[148:149], v[148:149], v[150:151]
	v_lshlrev_b32_e32 v150, 16, v91
	v_and_b32_e32 v151, 0xffff0000, v91
	v_pk_fma_f32 v[150:151], v[106:107], v[150:151], v[152:153]
	v_lshlrev_b32_e32 v152, 16, v95
	v_and_b32_e32 v153, 0xffff0000, v95
	v_pk_fma_f32 v[150:151], v[118:119], v[152:153], v[150:151]
	v_lshlrev_b32_e32 v152, 16, v47
	v_and_b32_e32 v153, 0xffff0000, v47
	v_pk_mul_f32 v[148:149], v[130:131], v[148:149] op_sel_hi:[0,1]
	v_pk_fma_f32 v[150:151], v[126:127], v[152:153], v[150:151]
	v_cvt_pk_bf16_f32 v148, v148, v149
	v_mul_f32_e32 v139, 0xbfb8aa3b, v151
	v_mul_f32_e32 v149, 0xbfb8aa3b, v150
	v_exp_f32_e32 v139, v139
	v_exp_f32_e32 v149, v149
	v_add_f32_e32 v139, 1.0, v139
	v_add_f32_e32 v149, 1.0, v149
	v_rcp_f32_e32 v153, v139
	v_rcp_f32_e32 v152, v149
	s_nop 0
	v_and_b32_e32 v139, 0xffff0000, v52
	v_pk_mul_f32 v[150:151], v[150:151], v[152:153]
	s_nop 0
	v_pk_mul_f32 v[150:151], v[130:131], v[150:151] op_sel_hi:[0,1]
	v_cvt_pk_bf16_f32 v149, v150, v151
	ds_write_b128 v138, v[146:149] offset:34816
	v_lshlrev_b32_e32 v138, 16, v52
	s_nop 0
	v_lshlrev_b32_e32 v146, 16, v58
	v_and_b32_e32 v147, 0xffff0000, v58
	v_pk_fma_f32 v[120:121], v[120:121], v[138:139], 0 op_sel_hi:[1,1,0]
	s_nop 0
	v_pk_fma_f32 v[112:113], v[112:113], v[146:147], v[120:121]
	s_nop 0
	v_lshlrev_b32_e32 v120, 16, v66
	v_and_b32_e32 v121, 0xffff0000, v66
	v_pk_fma_f32 v[100:101], v[100:101], v[120:121], v[112:113]
	s_nop 0
	v_lshlrev_b32_e32 v112, 16, v72
	v_and_b32_e32 v113, 0xffff0000, v72
	v_pk_fma_f32 v[100:101], v[108:109], v[112:113], v[100:101]
	v_lshlrev_b32_e32 v108, 16, v53
	v_mul_f32_e32 v112, 0xbfb8aa3b, v101
	v_exp_f32_e32 v120, v112
	v_mul_f32_e32 v112, 0xbfb8aa3b, v100
	v_exp_f32_e32 v121, v112
	v_and_b32_e32 v109, 0xffff0000, v53
	v_pk_fma_f32 v[108:109], v[122:123], v[108:109], 0 op_sel_hi:[1,1,0]
	v_lshlrev_b32_e32 v112, 16, v59
	v_and_b32_e32 v113, 0xffff0000, v59
	v_pk_fma_f32 v[108:109], v[114:115], v[112:113], v[108:109]
	v_add_f32_e32 v113, 1.0, v120
	v_rcp_f32_e32 v115, v113
	v_add_f32_e32 v113, 1.0, v121
	v_lshlrev_b32_e32 v120, 16, v67
	v_and_b32_e32 v121, 0xffff0000, v67
	v_lshlrev_b32_e32 v122, 16, v73
	v_and_b32_e32 v123, 0xffff0000, v73
	v_pk_fma_f32 v[102:103], v[102:103], v[120:121], v[108:109]
	v_rcp_f32_e32 v114, v113
	v_pk_fma_f32 v[102:103], v[110:111], v[122:123], v[102:103]
	ds_read_b32 v112, v137
	v_mul_f32_e32 v108, 0xbfb8aa3b, v103
	v_exp_f32_e32 v108, v108
	v_mul_f32_e32 v109, 0xbfb8aa3b, v102
	v_exp_f32_e32 v110, v109
	v_and_b32_e32 v111, 0xffff0000, v60
	v_add_f32_e32 v108, 1.0, v108
	v_rcp_f32_e32 v109, v108
	v_add_f32_e32 v108, 1.0, v110
	v_rcp_f32_e32 v108, v108
	v_lshlrev_b32_e32 v110, 16, v60
	v_pk_mul_f32 v[100:101], v[100:101], v[114:115]
	v_lshlrev_b32_e32 v114, 16, v68
	v_pk_mul_f32 v[102:103], v[102:103], v[108:109]
	v_lshlrev_b32_e32 v108, 16, v54
	v_and_b32_e32 v109, 0xffff0000, v54
	v_pk_fma_f32 v[96:97], v[96:97], v[108:109], 0 op_sel_hi:[1,1,0]
	v_and_b32_e32 v115, 0xffff0000, v68
	v_pk_fma_f32 v[96:97], v[104:105], v[110:111], v[96:97]
	v_lshlrev_b32_e32 v120, 16, v74
	v_and_b32_e32 v121, 0xffff0000, v74
	v_pk_fma_f32 v[96:97], v[116:117], v[114:115], v[96:97]
	s_waitcnt lgkmcnt(0)
	v_pk_mul_f32 v[100:101], v[100:101], v[112:113] op_sel_hi:[1,0]
	v_pk_fma_f32 v[96:97], v[124:125], v[120:121], v[96:97]
	v_cvt_pk_bf16_f32 v100, v100, v101
	v_mul_f32_e32 v101, 0xbfb8aa3b, v97
	v_exp_f32_e32 v104, v101
	v_mul_f32_e32 v101, 0xbfb8aa3b, v96
	v_exp_f32_e32 v105, v101
	v_pk_mul_f32 v[102:103], v[112:113], v[102:103] op_sel_hi:[0,1]
	v_cvt_pk_bf16_f32 v101, v102, v103
	v_add_f32_e32 v102, 1.0, v104
	v_rcp_f32_e32 v103, v102
	v_add_f32_e32 v102, 1.0, v105
	v_lshlrev_b32_e32 v104, 16, v55
	v_and_b32_e32 v105, 0xffff0000, v55
	v_lshlrev_b32_e32 v108, 16, v61
	v_and_b32_e32 v109, 0xffff0000, v61
	v_pk_fma_f32 v[98:99], v[98:99], v[104:105], 0 op_sel_hi:[1,1,0]
	v_lshlrev_b32_e32 v110, 16, v69
	v_and_b32_e32 v111, 0xffff0000, v69
	v_pk_fma_f32 v[98:99], v[106:107], v[108:109], v[98:99]
	v_lshlrev_b32_e32 v114, 16, v75
	v_and_b32_e32 v115, 0xffff0000, v75
	v_pk_fma_f32 v[98:99], v[118:119], v[110:111], v[98:99]
	v_rcp_f32_e32 v102, v102
	v_pk_fma_f32 v[98:99], v[126:127], v[114:115], v[98:99]
	v_lshlrev_b32_e32 v118, 4, v132
	v_mul_f32_e32 v104, 0xbfb8aa3b, v99
	v_exp_f32_e32 v104, v104
	v_mul_f32_e32 v105, 0xbfb8aa3b, v98
	v_exp_f32_e32 v106, v105
	v_pk_mul_f32 v[96:97], v[96:97], v[102:103]
	v_add_f32_e32 v104, 1.0, v104
	v_rcp_f32_e32 v105, v104
	v_add_f32_e32 v104, 1.0, v106
	v_rcp_f32_e32 v104, v104
	v_pk_mul_f32 v[96:97], v[112:113], v[96:97] op_sel_hi:[0,1]
	v_cvt_pk_bf16_f32 v102, v96, v97
	v_pk_mul_f32 v[96:97], v[98:99], v[104:105]
	s_nop 0
	v_pk_mul_f32 v[96:97], v[112:113], v[96:97] op_sel_hi:[0,1]
	v_cvt_pk_bf16_f32 v103, v96, v97
	ds_write_b128 v136, v[100:103] offset:34816
	s_cbranch_scc1 .LBB0_374
	s_lshr_b32 s20, s31, 8
	s_lshl_b32 s4, s31, 6
	s_and_b32 s30, s4, 0x7c0
	s_lshl_b64 s[6:7], s[20:21], 11
	s_or_b32 s4, s6, s30
	s_add_u32 s8, s4, -3
	s_addc_u32 s9, s7, 0x3ffff
	v_add_u32_e32 v8, s30, v134
	v_ashrrev_i32_e32 v135, 31, v134
	v_add_u32_e32 v11, s30, v128
	v_ashrrev_i32_e32 v129, 31, v128
	v_lshl_add_u64 v[0:1], s[8:9], 0, v[134:135]
	v_mov_b32_e32 v9, s4
	v_cmp_lt_i32_e64 s[4:5], 2, v8
	v_mov_b32_e32 v10, s7
	v_lshl_add_u64 v[4:5], s[8:9], 0, v[128:129]
	v_cmp_lt_i32_e64 s[6:7], 2, v11
	v_cndmask_b32_e64 v2, v9, v0, s[4:5]
	v_cndmask_b32_e64 v3, v10, v1, s[4:5]
	v_cndmask_b32_e64 v6, v9, v4, s[6:7]
	v_cndmask_b32_e64 v7, v10, v5, s[6:7]
	v_lshlrev_b64 v[6:7], 14, v[6:7]
	s_lshl_b32 s8, s31, 3
	v_lshlrev_b64 v[2:3], 14, v[2:3]
	v_lshl_add_u64 v[6:7], s[66:67], 0, v[6:7]
	s_and_b32 s20, s8, 0x700
	v_lshl_add_u64 v[2:3], s[66:67], 0, v[2:3]
	v_lshl_add_u64 v[6:7], v[6:7], 0, s[20:21]
	v_and_b32_e32 v130, 0xf0, v118
	v_lshl_add_u64 v[2:3], v[2:3], 0, s[20:21]
	v_lshl_add_u64 v[44:45], v[6:7], 0, v[130:131]
	v_lshl_add_u64 v[6:7], v[4:5], 0, 1
	v_cmp_lt_i32_e64 s[8:9], 1, v11
	v_lshl_add_u64 v[56:57], v[2:3], 0, v[130:131]
	v_lshl_add_u64 v[2:3], v[0:1], 0, 1
	v_cmp_lt_i32_e64 s[14:15], 1, v8
	v_cndmask_b32_e64 v6, v9, v6, s[8:9]
	v_cndmask_b32_e64 v7, v10, v7, s[8:9]
	v_cndmask_b32_e64 v2, v9, v2, s[14:15]
	v_cndmask_b32_e64 v3, v10, v3, s[14:15]
	v_lshlrev_b64 v[6:7], 14, v[6:7]
	v_lshlrev_b64 v[2:3], 14, v[2:3]
	v_lshl_add_u64 v[6:7], s[66:67], 0, v[6:7]
	v_lshl_add_u64 v[2:3], s[66:67], 0, v[2:3]
	v_lshl_add_u64 v[6:7], v[6:7], 0, s[20:21]
	v_lshl_add_u64 v[2:3], v[2:3], 0, s[20:21]
	v_lshl_add_u64 v[46:47], v[6:7], 0, v[130:131]
	v_lshl_add_u64 v[6:7], v[4:5], 0, 2
	v_cmp_lt_i32_e64 s[10:11], 0, v11
	v_lshl_add_u64 v[4:5], v[4:5], 0, 3
	v_cmp_lt_i32_e64 s[12:13], -1, v11
	v_lshl_add_u64 v[58:59], v[2:3], 0, v[130:131]
	v_lshl_add_u64 v[2:3], v[0:1], 0, 2
	v_cmp_lt_i32_e64 s[16:17], 0, v8
	v_lshl_add_u64 v[0:1], v[0:1], 0, 3
	v_cmp_lt_i32_e64 s[18:19], -1, v8
	v_cndmask_b32_e64 v6, v9, v6, s[10:11]
	v_cndmask_b32_e64 v7, v10, v7, s[10:11]
	v_cndmask_b32_e64 v4, v9, v4, s[12:13]
	v_cndmask_b32_e64 v5, v10, v5, s[12:13]
	v_cndmask_b32_e64 v2, v9, v2, s[16:17]
	v_cndmask_b32_e64 v3, v10, v3, s[16:17]
	v_cndmask_b32_e64 v0, v9, v0, s[18:19]
	v_cndmask_b32_e64 v1, v10, v1, s[18:19]
	v_lshlrev_b64 v[6:7], 14, v[6:7]
	v_lshlrev_b64 v[4:5], 14, v[4:5]
	v_lshlrev_b64 v[2:3], 14, v[2:3]
	v_lshlrev_b64 v[0:1], 14, v[0:1]
	v_lshl_add_u64 v[6:7], s[66:67], 0, v[6:7]
	v_lshl_add_u64 v[4:5], s[66:67], 0, v[4:5]
	v_lshl_add_u64 v[2:3], s[66:67], 0, v[2:3]
	v_lshl_add_u64 v[0:1], s[66:67], 0, v[0:1]
	v_lshl_add_u64 v[6:7], v[6:7], 0, s[20:21]
	v_lshl_add_u64 v[4:5], v[4:5], 0, s[20:21]
	v_lshl_add_u64 v[2:3], v[2:3], 0, s[20:21]
	v_lshl_add_u64 v[0:1], v[0:1], 0, s[20:21]
	v_lshl_add_u64 v[48:49], v[6:7], 0, v[130:131]
	v_lshl_add_u64 v[50:51], v[4:5], 0, v[130:131]
	v_lshl_add_u64 v[66:67], v[2:3], 0, v[130:131]
	v_lshl_add_u64 v[68:69], v[0:1], 0, v[130:131]
	global_load_dwordx4 v[40:43], v[44:45], off
	global_load_dwordx4 v[82:85], v[44:45], off offset:2048
	global_load_dwordx4 v[62:65], v[46:47], off
	global_load_dwordx4 v[76:79], v[46:47], off offset:2048
	global_load_dwordx4 v[180:183], v[48:49], off
	global_load_dwordx4 v[86:89], v[48:49], off offset:2048
	global_load_dwordx4 v[16:19], v[50:51], off
	global_load_dwordx4 v[20:23], v[50:51], off offset:2048
	global_load_dwordx4 v[0:3], v[56:57], off
	global_load_dwordx4 v[24:27], v[56:57], off offset:2048
	global_load_dwordx4 v[4:7], v[58:59], off
	global_load_dwordx4 v[28:31], v[58:59], off offset:2048
	global_load_dwordx4 v[8:11], v[66:67], off
	global_load_dwordx4 v[32:35], v[66:67], off offset:2048
	global_load_dwordx4 v[12:15], v[68:69], off
	global_load_dwordx4 v[36:39], v[68:69], off offset:2048
	v_add_co_u32_e32 v44, vcc, s37, v44
	v_mov_b32_e32 v129, 0
	s_nop 0
	v_addc_co_u32_e32 v45, vcc, 0, v45, vcc
	v_add_co_u32_e32 v46, vcc, s37, v46
	v_mov_b32_e32 v135, 0
	s_nop 0
	v_addc_co_u32_e32 v47, vcc, 0, v47, vcc
	global_load_dwordx4 v[92:95], v[44:45], off
	global_load_dwordx4 v[52:55], v[46:47], off
	v_add_co_u32_e32 v44, vcc, s37, v48
	s_nop 1
	v_addc_co_u32_e32 v45, vcc, 0, v49, vcc
	v_add_co_u32_e32 v46, vcc, s37, v50
	s_nop 1
	v_addc_co_u32_e32 v47, vcc, 0, v51, vcc
	v_add_co_u32_e32 v48, vcc, s37, v56
	global_load_dwordx4 v[176:179], v[44:45], off
	s_nop 0
	global_load_dwordx4 v[44:47], v[46:47], off
	v_addc_co_u32_e32 v49, vcc, 0, v57, vcc
	v_add_co_u32_e32 v50, vcc, s37, v58
	s_nop 1
	v_addc_co_u32_e32 v51, vcc, 0, v59, vcc
	global_load_dwordx4 v[172:175], v[48:49], off
	global_load_dwordx4 v[58:61], v[50:51], off
	v_add_co_u32_e32 v48, vcc, 0x1000, v66
	s_nop 1
	v_addc_co_u32_e32 v49, vcc, 0, v67, vcc
	v_add_co_u32_e32 v50, vcc, 0x1000, v68
	s_nop 1
	v_addc_co_u32_e32 v51, vcc, 0, v69, vcc
	global_load_dwordx4 v[66:69], v[48:49], off
	global_load_dwordx4 v[72:75], v[50:51], off
	s_and_saveexec_b64 s[34:35], s[2:3]
	s_cbranch_execz .LBB0_373
	s_lshr_b32 s20, s31, 5
	s_mov_b32 s31, s21
	s_lshl_b64 s[90:91], s[20:21], 11
	s_or_b64 s[30:31], s[90:91], s[30:31]
	v_lshl_add_u64 v[48:49], s[30:31], 0, v[132:133]
	v_lshlrev_b64 v[48:49], 2, v[48:49]
	v_lshl_add_u64 v[50:51], s[72:73], 0, v[48:49]
	v_lshl_add_u64 v[48:49], s[74:75], 0, v[48:49]
	global_load_dword v129, v[48:49], off
	global_load_dword v135, v[50:51], off

.LBB0_521:
	s_or_b64 exec, exec, s[2:3]
	v_or_b32_e32 v102, v96, v142
	s_movk_i32 s2, 0x440
	v_mad_u32_u24 v97, v121, s2, v102
	s_waitcnt lgkmcnt(0)
	s_barrier
	s_and_b32 s4, s65, 31
	s_lshl_b32 s4, s4, 6
	v_lshrrev_b32_e32 v170, 4, v198
	v_add_u32_e32 v170, s4, v170
	v_cmp_lt_i32_e64 s[6:7], 2, v170
	v_cmp_lt_i32_e64 s[8:9], 1, v170
	v_cmp_lt_i32_e64 s[10:11], 0, v170
	s_nop 1
	s_waitcnt vmcnt(23)
	v_cndmask_b32_e64 v43, 0, v43, s[6:7]
	v_cndmask_b32_e64 v50, 0, v42, s[6:7]
	v_cndmask_b32_e64 v41, 0, v41, s[6:7]
	v_cndmask_b32_e64 v40, 0, v40, s[6:7]
	s_waitcnt vmcnt(21)
	v_cndmask_b32_e64 v51, 0, v65, s[8:9]
	v_cndmask_b32_e64 v56, 0, v64, s[8:9]
	v_cndmask_b32_e64 v49, 0, v63, s[8:9]
	v_cndmask_b32_e64 v42, 0, v62, s[8:9]
	s_waitcnt vmcnt(19)
	v_cndmask_b32_e64 v63, 0, v183, s[10:11]
	v_cndmask_b32_e64 v64, 0, v182, s[10:11]
	v_cndmask_b32_e64 v57, 0, v181, s[10:11]
	v_cndmask_b32_e64 v48, 0, v180, s[10:11]
	s_waitcnt vmcnt(17)
	s_waitcnt vmcnt(15)
	s_waitcnt vmcnt(13)
	s_waitcnt vmcnt(11)
	s_waitcnt vmcnt(9)
	v_cndmask_b32_e64 v71, 0, v85, s[6:7]
	v_cndmask_b32_e64 v80, 0, v84, s[6:7]
	v_cndmask_b32_e64 v65, 0, v83, s[6:7]
	v_cndmask_b32_e64 v62, 0, v82, s[6:7]
	v_cndmask_b32_e64 v79, 0, v79, s[8:9]
	v_cndmask_b32_e64 v84, 0, v78, s[8:9]
	v_cndmask_b32_e64 v77, 0, v77, s[8:9]
	v_cndmask_b32_e64 v70, 0, v76, s[8:9]
	v_cndmask_b32_e64 v83, 0, v89, s[10:11]
	v_cndmask_b32_e64 v88, 0, v88, s[10:11]
	v_cndmask_b32_e64 v81, 0, v87, s[10:11]
	v_cndmask_b32_e64 v76, 0, v86, s[10:11]
	s_waitcnt vmcnt(8)
	s_waitcnt vmcnt(7)
	v_cndmask_b32_e64 v87, 0, v95, s[6:7]
	v_cndmask_b32_e64 v90, 0, v94, s[6:7]
	v_cndmask_b32_e64 v85, 0, v93, s[6:7]
	v_cndmask_b32_e64 v78, 0, v92, s[6:7]
	s_waitcnt vmcnt(6)
	v_cndmask_b32_e64 v91, 0, v55, s[8:9]
	v_cndmask_b32_e64 v92, 0, v54, s[8:9]
	v_cndmask_b32_e64 v89, 0, v53, s[8:9]
	v_cndmask_b32_e64 v82, 0, v52, s[8:9]
	s_waitcnt vmcnt(5)
	v_cndmask_b32_e64 v95, 0, v179, s[10:11]
	v_cndmask_b32_e64 v94, 0, v178, s[10:11]
	v_cndmask_b32_e64 v93, 0, v177, s[10:11]
	v_cndmask_b32_e64 v86, 0, v176, s[10:11]
	s_waitcnt vmcnt(4)
	s_waitcnt vmcnt(3)
	v_mov_b32_e32 v55, v175
	v_mov_b32_e32 v54, v174
	v_mov_b32_e32 v53, v173
	v_mov_b32_e32 v52, v172
	s_waitcnt vmcnt(2)
	s_waitcnt vmcnt(1)
	s_waitcnt vmcnt(0)
	v_lshl_add_u32 v97, v97, 1, 0
	ds_read_u16 v106, v97 offset:34816
	ds_read_u16 v107, v97 offset:35088
	ds_read_u16 v108, v97 offset:35360
	ds_read_u16 v109, v97 offset:35632
	ds_read_u16 v104, v97 offset:35904
	ds_read_u16 v110, v97 offset:36176
	ds_read_u16 v105, v97 offset:36448
	ds_read_u16 v111, v97 offset:36720
	ds_read_u16 v114, v97 offset:52224
	ds_read_u16 v122, v97 offset:52496
	ds_read_u16 v115, v97 offset:52768
	ds_read_u16 v123, v97 offset:53040
	ds_read_u16 v116, v97 offset:53312
	ds_read_u16 v124, v97 offset:53584
	ds_read_u16 v117, v97 offset:53856
	ds_read_u16 v125, v97 offset:54128
	ds_read_u16 v126, v97 offset:43520
	ds_read_u16 v127, v97 offset:43792
	ds_read_u16 v128, v97 offset:44064
	ds_read_u16 v133, v97 offset:44336
	ds_read_u16 v134, v97 offset:44608
	ds_read_u16 v146, v97 offset:44880
	ds_read_u16 v147, v97 offset:45152
	ds_read_u16 v148, v97 offset:45424
	ds_read_u16 v149, v97 offset:60928
	ds_read_u16 v150, v97 offset:61200
	ds_read_u16 v151, v97 offset:61472
	ds_read_u16 v152, v97 offset:61744
	ds_read_u16 v153, v97 offset:62016
	ds_read_u16 v154, v97 offset:62288
	ds_read_u16 v155, v97 offset:62560
	ds_read_u16 v157, v97 offset:62832
	v_mul_u32_u24_e32 v97, 0x90, v142
	v_add3_u32 v158, s1, v120, v97
	ds_read_b128 v[98:101], v158
	v_ashrrev_i32_e32 v103, 31, v102
	v_lshlrev_b64 v[120:121], 7, v[102:103]
	s_waitcnt lgkmcnt(14)
	v_perm_b32 v105, v111, v105, s59
	v_perm_b32 v104, v110, v104, s59
	v_perm_b32 v103, v109, v108, s59
	v_perm_b32 v102, v107, v106, s59
	ds_read_b128 v[106:109], v158 offset:2304
	s_ashr_i32 s25, s24, 31
	s_waitcnt lgkmcnt(1)
	v_mfma_f32_16x16x32_bf16 v[110:113], v[98:101], v[102:105], 0
	v_perm_b32 v117, v125, v117, s59
	v_perm_b32 v116, v124, v116, s59
	v_perm_b32 v115, v123, v115, s59
	v_perm_b32 v114, v122, v114, s59
	s_add_u32 s2, s46, s28
	v_ashrrev_i32_e32 v97, 31, v96
	v_mfma_f32_16x16x32_bf16 v[98:101], v[98:101], v[114:117], 0
	s_addc_u32 s3, s47, s29
	v_cvt_pk_bf16_f32 v110, v110, v111
	v_cvt_pk_bf16_f32 v111, v112, v113
	v_lshl_add_u64 v[112:113], s[2:3], 0, v[120:121]
	v_lshlrev_b32_e32 v120, 1, v119
	v_mov_b32_e32 v121, v131
	v_lshl_add_u64 v[96:97], v[96:97], 1, s[82:83]
	s_lshl_b64 s[2:3], s[24:25], 14
	v_lshl_add_u64 v[136:137], v[112:113], 0, v[120:121]
	v_lshl_add_u64 v[138:139], v[96:97], 0, v[130:131]
	v_lshl_or_b32 v142, v119, 8, s2
	v_mov_b32_e32 v143, s3
	global_store_dwordx2 v[136:137], v[110:111], off
	v_cvt_pk_bf16_f32 v96, -v98, s0
	v_lshl_add_u64 v[110:111], v[138:139], 0, v[142:143]
	global_store_short v[110:111], v96, off
	v_cvt_pk_bf16_f32 v96, -v99, s0
	global_store_short v[110:111], v96, off offset:256
	s_waitcnt lgkmcnt(0)
	v_mfma_f32_16x16x32_bf16 v[96:99], v[106:109], v[102:105], 0
	v_cvt_pk_bf16_f32 v100, -v100, s0
	global_store_short v[110:111], v100, off offset:512
	v_cvt_pk_bf16_f32 v100, -v101, s0
	v_mfma_f32_16x16x32_bf16 v[106:109], v[106:109], v[114:117], 0
	global_store_short v[110:111], v100, off offset:768
	s_nop 2
	v_cvt_pk_bf16_f32 v96, v96, v97
	v_cvt_pk_bf16_f32 v97, v98, v99
	global_store_dwordx2 v[136:137], v[96:97], off offset:32
	v_or_b32_e32 v96, 0x1000, v142
	v_mov_b32_e32 v97, s3
	v_cvt_pk_bf16_f32 v98, -v106, s0
	v_lshl_add_u64 v[96:97], v[138:139], 0, v[96:97]
	global_store_short v[96:97], v98, off
	v_or_b32_e32 v96, 0x1100, v142
	v_mov_b32_e32 v97, s3
	v_cvt_pk_bf16_f32 v98, -v107, s0
	v_lshl_add_u64 v[96:97], v[138:139], 0, v[96:97]
	global_store_short v[96:97], v98, off
	ds_read_b128 v[96:99], v158 offset:4608
	v_or_b32_e32 v100, 0x1200, v142
	v_mov_b32_e32 v101, s3
	v_cvt_pk_bf16_f32 v106, -v108, s0
	v_lshl_add_u64 v[100:101], v[138:139], 0, v[100:101]
	global_store_short v[100:101], v106, off
	v_cvt_pk_bf16_f32 v119, -v109, s0
	ds_read_b128 v[106:109], v158 offset:4672
	s_waitcnt lgkmcnt(1)
	v_mfma_f32_16x16x32_bf16 v[110:113], v[96:99], v[102:105], 0
	v_perm_b32 v123, v148, v147, s59
	v_perm_b32 v122, v146, v134, s59
	v_perm_b32 v121, v133, v128, s59
	v_mfma_f32_16x16x32_bf16 v[96:99], v[96:99], v[114:117], 0
	v_perm_b32 v120, v127, v126, s59
	v_perm_b32 v127, v157, v155, s59
	v_perm_b32 v126, v154, v153, s59
	v_perm_b32 v125, v152, v151, s59
	v_perm_b32 v124, v150, v149, s59
	s_waitcnt lgkmcnt(0)
	v_mfma_f32_16x16x32_bf16 v[110:113], v[106:109], v[120:123], v[110:113]
	v_or_b32_e32 v100, 0x1300, v142
	v_mov_b32_e32 v101, s3
	v_lshl_add_u64 v[100:101], v[138:139], 0, v[100:101]
	v_mfma_f32_16x16x32_bf16 v[96:99], v[106:109], v[124:127], v[96:99]
	ds_read_b128 v[106:109], v158 offset:6912
	global_store_short v[100:101], v119, off
	s_nop 1
	v_cvt_pk_bf16_f32 v100, v110, v111
	v_cvt_pk_bf16_f32 v101, v112, v113
	ds_read_b128 v[110:113], v158 offset:6976
	global_store_dwordx2 v[136:137], v[100:101], off offset:64
	v_or_b32_e32 v100, 0x2000, v142
	v_mov_b32_e32 v101, s3
	v_cvt_pk_bf16_f32 v96, -v96, s0
	v_lshl_add_u64 v[100:101], v[138:139], 0, v[100:101]
	global_store_short v[100:101], v96, off
	v_cvt_pk_bf16_f32 v100, -v97, s0
	v_or_b32_e32 v96, 0x2100, v142
	v_mov_b32_e32 v97, s3
	v_lshl_add_u64 v[96:97], v[138:139], 0, v[96:97]
	global_store_short v[96:97], v100, off
	s_waitcnt lgkmcnt(1)
	v_mfma_f32_16x16x32_bf16 v[100:103], v[106:109], v[102:105], 0
	v_or_b32_e32 v96, 0x2200, v142
	v_mov_b32_e32 v97, s3
	v_cvt_pk_bf16_f32 v98, -v98, s0
	v_mfma_f32_16x16x32_bf16 v[104:107], v[106:109], v[114:117], 0
	v_lshl_add_u64 v[96:97], v[138:139], 0, v[96:97]
	global_store_short v[96:97], v98, off
	v_cvt_pk_bf16_f32 v114, -v99, s0
	v_or_b32_e32 v108, 0x2300, v142
	s_waitcnt lgkmcnt(0)
	v_mfma_f32_16x16x32_bf16 v[96:99], v[110:113], v[120:123], v[100:103]
	v_mov_b32_e32 v109, s3
	v_and_b32_e32 v116, 48, v118
	s_add_u32 s2, s44, s28
	v_lshl_add_u64 v[100:101], v[138:139], 0, v[108:109]
	global_store_short v[100:101], v114, off
	v_mfma_f32_16x16x32_bf16 v[100:103], v[110:113], v[124:127], v[104:107]
	s_nop 1
	v_cvt_pk_bf16_f32 v96, v96, v97
	v_cvt_pk_bf16_f32 v97, v98, v99
	global_store_dwordx2 v[136:137], v[96:97], off offset:96
	v_or_b32_e32 v96, 0x3000, v142
	v_mov_b32_e32 v97, s3
	s_nop 0
	v_cvt_pk_bf16_f32 v98, -v100, s0
	v_lshl_add_u64 v[96:97], v[138:139], 0, v[96:97]
	global_store_short v[96:97], v98, off
	v_or_b32_e32 v96, 0x3100, v142
	v_mov_b32_e32 v97, s3
	v_cvt_pk_bf16_f32 v98, -v101, s0
	v_lshl_add_u64 v[96:97], v[138:139], 0, v[96:97]
	global_store_short v[96:97], v98, off
	v_or_b32_e32 v96, 0x3200, v142
	v_mov_b32_e32 v97, s3
	v_cvt_pk_bf16_f32 v98, -v102, s0
	v_lshl_add_u64 v[96:97], v[138:139], 0, v[96:97]
	v_or_b32_e32 v142, 0x3300, v142
	global_store_short v[96:97], v98, off
	v_cvt_pk_bf16_f32 v98, -v103, s0
	v_lshl_add_u64 v[96:97], v[138:139], 0, v[142:143]
	global_store_short v[96:97], v98, off
	v_lshl_add_u32 v96, v116, 2, 0
	v_add_u32_e32 v108, 0x1f700, v96
	ds_read_b128 v[96:99], v108
	v_ashrrev_i32_e32 v112, 2, v132
	v_lshlrev_b32_e32 v100, 1, v112
	v_mul_u32_u24_e32 v101, 0x110, v116
	v_add3_u32 v113, 0, v100, v101
	s_waitcnt lgkmcnt(0)
	v_sub_f32_e32 v96, v141, v96
	v_sub_f32_e32 v97, v141, v97
	v_mul_f32_e32 v96, 0x3fb8aa3b, v96
	v_mul_f32_e32 v97, 0x3fb8aa3b, v97
	v_exp_f32_e32 v96, v96
	v_exp_f32_e32 v97, v97
	ds_read_b128 v[100:103], v108 offset:16
	ds_read_b128 v[104:107], v108 offset:32
	ds_read_b128 v[108:111], v108 offset:48
	ds_read_u16 v114, v113 offset:17408
	ds_read_u16 v115, v113 offset:17680
	ds_read_u16 v117, v113 offset:17952
	ds_read_u16 v118, v113 offset:18224
	ds_read_u16 v119, v113 offset:18496
	ds_read_u16 v120, v113 offset:18768
	ds_read_u16 v121, v113 offset:19040
	ds_read_u16 v122, v113 offset:19312
	s_waitcnt lgkmcnt(6)
	v_lshlrev_b32_e32 v115, 16, v115
	v_lshlrev_b32_e32 v114, 16, v114
	v_pk_mul_f32 v[96:97], v[96:97], v[114:115]
	v_sub_f32_e32 v98, v141, v98
	v_sub_f32_e32 v99, v141, v99
	v_cvt_pk_bf16_f32 v96, v96, v97
	v_sub_f32_e32 v97, v141, v100
	v_mul_f32_e32 v98, 0x3fb8aa3b, v98
	v_mul_f32_e32 v99, 0x3fb8aa3b, v99
	v_mul_f32_e32 v97, 0x3fb8aa3b, v97
	v_exp_f32_e32 v98, v98
	v_exp_f32_e32 v99, v99
	v_exp_f32_e32 v100, v97
	v_sub_f32_e32 v97, v141, v101
	v_mul_f32_e32 v97, 0x3fb8aa3b, v97
	v_exp_f32_e32 v101, v97
	s_waitcnt lgkmcnt(4)
	v_lshlrev_b32_e32 v115, 16, v118
	v_lshlrev_b32_e32 v114, 16, v117
	v_pk_mul_f32 v[98:99], v[98:99], v[114:115]
	s_addc_u32 s3, s45, s29
	v_cvt_pk_bf16_f32 v97, v98, v99
	s_waitcnt lgkmcnt(2)
	v_lshlrev_b32_e32 v99, 16, v120
	v_lshlrev_b32_e32 v98, 16, v119
	v_pk_mul_f32 v[98:99], v[100:101], v[98:99]
	v_sub_f32_e32 v100, v141, v102
	v_sub_f32_e32 v101, v141, v103
	v_mul_f32_e32 v100, 0x3fb8aa3b, v100
	v_mul_f32_e32 v101, 0x3fb8aa3b, v101
	v_exp_f32_e32 v100, v100
	v_exp_f32_e32 v101, v101
	s_waitcnt lgkmcnt(0)
	v_lshlrev_b32_e32 v103, 16, v122
	v_lshlrev_b32_e32 v102, 16, v121
	v_cvt_pk_bf16_f32 v98, v98, v99
	v_pk_mul_f32 v[100:101], v[100:101], v[102:103]
	v_lshlrev_b32_e32 v130, 1, v116
	v_cvt_pk_bf16_f32 v99, v100, v101
	v_sub_f32_e32 v100, v141, v104
	v_sub_f32_e32 v101, v141, v105
	v_mul_f32_e32 v100, 0x3fb8aa3b, v100
	v_mul_f32_e32 v101, 0x3fb8aa3b, v101
	v_exp_f32_e32 v100, v100
	v_exp_f32_e32 v101, v101
	ds_read_u16 v102, v113 offset:19584
	ds_read_u16 v103, v113 offset:19856
	ds_read_u16 v104, v113 offset:20128
	ds_read_u16 v105, v113 offset:20400
	ds_read_u16 v114, v113 offset:20672
	ds_read_u16 v115, v113 offset:20944
	ds_read_u16 v117, v113 offset:21216
	ds_read_u16 v113, v113 offset:21488
	s_waitcnt lgkmcnt(6)
	v_lshlrev_b32_e32 v103, 16, v103
	v_lshlrev_b32_e32 v102, 16, v102
	v_pk_mul_f32 v[100:101], v[100:101], v[102:103]
	v_sub_f32_e32 v102, v141, v106
	v_sub_f32_e32 v103, v141, v107
	v_mul_f32_e32 v102, 0x3fb8aa3b, v102
	v_mul_f32_e32 v103, 0x3fb8aa3b, v103
	v_exp_f32_e32 v102, v102
	v_exp_f32_e32 v103, v103
	v_cvt_pk_bf16_f32 v100, v100, v101
	v_sub_f32_e32 v101, v141, v108
	s_waitcnt lgkmcnt(4)
	v_lshlrev_b32_e32 v105, 16, v105
	v_lshlrev_b32_e32 v104, 16, v104
	v_mul_f32_e32 v101, 0x3fb8aa3b, v101
	v_pk_mul_f32 v[102:103], v[102:103], v[104:105]
	v_exp_f32_e32 v104, v101
	v_sub_f32_e32 v101, v141, v109
	v_mul_f32_e32 v101, 0x3fb8aa3b, v101
	v_exp_f32_e32 v105, v101
	v_cvt_pk_bf16_f32 v101, v102, v103
	s_waitcnt lgkmcnt(2)
	v_lshlrev_b32_e32 v103, 16, v115
	v_lshlrev_b32_e32 v102, 16, v114
	v_pk_mul_f32 v[102:103], v[104:105], v[102:103]
	v_sub_f32_e32 v104, v141, v110
	v_sub_f32_e32 v105, v141, v111
	v_mul_f32_e32 v104, 0x3fb8aa3b, v104
	v_mul_f32_e32 v105, 0x3fb8aa3b, v105
	v_exp_f32_e32 v104, v104
	v_exp_f32_e32 v105, v105
	s_waitcnt lgkmcnt(0)
	v_lshlrev_b32_e32 v107, 16, v113
	v_lshlrev_b32_e32 v106, 16, v117
	v_ashrrev_i32_e32 v113, 31, v112
	v_pk_mul_f32 v[104:105], v[104:105], v[106:107]
	v_cvt_pk_bf16_f32 v102, v102, v103
	v_cvt_pk_bf16_f32 v103, v104, v105
	v_lshlrev_b64 v[104:105], 7, v[112:113]
	v_lshl_add_u64 v[104:105], s[2:3], 0, v[104:105]
	v_lshl_add_u64 v[104:105], v[104:105], 0, v[130:131]
	v_cmp_eq_u32_e32 vcc, 0, v132
	global_store_dwordx4 v[104:105], v[96:99], off
	global_store_dwordx4 v[104:105], v[100:103], off offset:16
	s_and_saveexec_b64 s[2:3], vcc
	s_cbranch_execz .LBB0_358
	v_mul_f32_e32 v96, 0x3fb8aa3b, v141
	v_exp_f32_e32 v96, v96
	s_lshl_b64 s[4:5], s[24:25], 2
	s_add_u32 s4, s80, s4
	s_addc_u32 s5, s81, s5
	global_store_dword v131, v96, s[4:5]
	s_branch .LBB0_358
